# NSA pass 2 (importance partials) rewritten by hand: two key blocks per step with all LDS reads batched, branch-free masked path, batched carries; same arithmetic order
# speedup vs baseline: 1.0088x; 1.0088x over previous
.Lp2k:
	s_andn2_b64 vcc, exec, s[8:9]
	s_cbranch_vccnz .Lp2k_inv
	s_cmp_lt_i32 s10, 1
	s_cbranch_scc1 .Lp2k_p0
	s_cmp_lg_u32 s10, 1
	s_cbranch_scc0 .Lp2k_p1
	ds_read_b128 v[56:59], v47
	ds_read_b128 v[64:67], v48
	ds_read_b128 v[60:63], v47 offset:2048
	ds_read_b128 v[68:71], v48 offset:2048
	ds_read_b32 v96, v193
	s_waitcnt lgkmcnt(1)
	v_mfma_f32_16x16x32_bf16 v[72:75], v[56:59], v[2:5], 0
	v_mfma_f32_16x16x32_bf16 v[76:79], v[60:63], v[2:5], 0
	v_mfma_f32_16x16x32_bf16 v[72:75], v[64:67], v[6:9], v[72:75]
	v_mfma_f32_16x16x32_bf16 v[76:79], v[68:71], v[6:9], v[76:79]
	v_mfma_f32_16x16x32_bf16 v[56:59], v[56:59], v[10:13], 0
	v_mfma_f32_16x16x32_bf16 v[60:63], v[60:63], v[10:13], 0
	v_mfma_f32_16x16x32_bf16 v[56:59], v[64:67], v[14:17], v[56:59]
	v_mfma_f32_16x16x32_bf16 v[60:63], v[68:71], v[14:17], v[60:63]
	s_waitcnt lgkmcnt(0)
	s_nop 7
	v_pk_fma_f32 v[80:81], v[72:73], s[36:37], v[96:97] op_sel_hi:[1,0,0]
	v_pk_fma_f32 v[82:83], v[74:75], s[36:37], v[96:97] op_sel_hi:[1,0,0]
	v_pk_fma_f32 v[84:85], v[76:77], s[36:37], v[96:97] op_sel_hi:[1,0,0]
	v_pk_fma_f32 v[86:87], v[78:79], s[36:37], v[96:97] op_sel_hi:[1,0,0]
	s_nop 0
	v_sub_f32_e32 v80, v80, v161
	v_sub_f32_e32 v81, v81, v161
	v_sub_f32_e32 v82, v82, v161
	v_sub_f32_e32 v83, v83, v161
	v_sub_f32_e32 v84, v84, v161
	v_sub_f32_e32 v85, v85, v161
	v_sub_f32_e32 v86, v86, v161
	v_sub_f32_e32 v87, v87, v161
	v_exp_f32_e32 v80, v80
	v_exp_f32_e32 v81, v81
	v_exp_f32_e32 v82, v82
	v_exp_f32_e32 v83, v83
	v_exp_f32_e32 v84, v84
	v_exp_f32_e32 v85, v85
	v_exp_f32_e32 v86, v86
	v_exp_f32_e32 v87, v87
	s_nop 0
	v_pk_fma_f32 v[88:89], v[56:57], s[36:37], v[96:97] op_sel_hi:[1,0,0]
	v_pk_fma_f32 v[90:91], v[58:59], s[36:37], v[96:97] op_sel_hi:[1,0,0]
	v_pk_fma_f32 v[92:93], v[60:61], s[36:37], v[96:97] op_sel_hi:[1,0,0]
	v_pk_fma_f32 v[94:95], v[62:63], s[36:37], v[96:97] op_sel_hi:[1,0,0]
	s_nop 0
	v_sub_f32_e32 v88, v88, v241
	v_sub_f32_e32 v89, v89, v241
	v_sub_f32_e32 v90, v90, v241
	v_sub_f32_e32 v91, v91, v241
	v_sub_f32_e32 v92, v92, v241
	v_sub_f32_e32 v93, v93, v241
	v_sub_f32_e32 v94, v94, v241
	v_sub_f32_e32 v95, v95, v241
	v_exp_f32_e32 v88, v88
	v_exp_f32_e32 v89, v89
	v_exp_f32_e32 v90, v90
	v_exp_f32_e32 v91, v91
	v_exp_f32_e32 v92, v92
	v_exp_f32_e32 v93, v93
	v_exp_f32_e32 v94, v94
	v_exp_f32_e32 v95, v95
	s_nop 0
	v_mov_b32_e32 v54, v81
	v_mov_b32_e32 v55, v83
	v_mov_b32_e32 v81, v82
	v_pk_mul_f32 v[54:55], v[34:35], v[54:55]
	s_nop 0
	v_pk_fma_f32 v[80:81], v[34:35], v[80:81], v[54:55]
	v_mov_b32_e32 v83, v55
	v_add_f32_e32 v72, v80, v81
	v_mov_b32_e32 v54, v85
	v_mov_b32_e32 v55, v87
	v_mov_b32_e32 v85, v86
	v_pk_mul_f32 v[54:55], v[34:35], v[54:55]
	s_nop 0
	v_pk_fma_f32 v[84:85], v[34:35], v[84:85], v[54:55]
	v_mov_b32_e32 v87, v55
	v_add_f32_e32 v73, v84, v85
	v_mov_b32_e32 v54, v89
	v_mov_b32_e32 v55, v91
	v_mov_b32_e32 v89, v90
	v_pk_mul_f32 v[54:55], v[36:37], v[54:55]
	s_nop 0
	v_pk_fma_f32 v[88:89], v[36:37], v[88:89], v[54:55]
	v_mov_b32_e32 v91, v55
	v_add_f32_e32 v74, v88, v89
	v_mov_b32_e32 v54, v93
	v_mov_b32_e32 v55, v95
	v_mov_b32_e32 v93, v94
	v_pk_mul_f32 v[54:55], v[36:37], v[54:55]
	s_nop 0
	v_pk_fma_f32 v[92:93], v[36:37], v[92:93], v[54:55]
	v_mov_b32_e32 v95, v55
	v_add_f32_e32 v75, v92, v93
	v_cndmask_b32_e64 v76, v83, v31, s[38:39]
	v_cndmask_b32_e64 v77, v87, v83, s[38:39]
	v_cndmask_b32_e64 v78, v91, v23, s[38:39]
	v_cndmask_b32_e64 v79, v95, v91, s[38:39]
	ds_bpermute_b32 v76, v0, v76
	ds_bpermute_b32 v77, v0, v77
	ds_bpermute_b32 v78, v0, v78
	ds_bpermute_b32 v79, v0, v79
	v_mov_b32_e32 v31, v87
	v_mov_b32_e32 v23, v95
	v_mov_b32_e32 v54, v49
	v_add_u32_e32 v55, 16, v49
	s_waitcnt lgkmcnt(0)
	v_add_f32_e32 v76, v72, v76
	v_add_f32_e32 v77, v73, v77
	v_add_f32_e32 v78, v74, v78
	v_add_f32_e32 v79, v75, v79
	ds_write2st64_b32 v54, v76, v78 offset1:4
	ds_write2st64_b32 v55, v77, v79 offset1:4
	ds_read_b128 v[56:59], v47 offset:4096
	ds_read_b128 v[64:67], v48 offset:4096
	ds_read_b128 v[60:63], v47 offset:6144
	ds_read_b128 v[68:71], v48 offset:6144
	ds_read_b32 v96, v193
	s_waitcnt lgkmcnt(1)
	v_mfma_f32_16x16x32_bf16 v[72:75], v[56:59], v[2:5], 0
	v_mfma_f32_16x16x32_bf16 v[76:79], v[60:63], v[2:5], 0
	v_mfma_f32_16x16x32_bf16 v[72:75], v[64:67], v[6:9], v[72:75]
	v_mfma_f32_16x16x32_bf16 v[76:79], v[68:71], v[6:9], v[76:79]
	v_mfma_f32_16x16x32_bf16 v[56:59], v[56:59], v[10:13], 0
	v_mfma_f32_16x16x32_bf16 v[60:63], v[60:63], v[10:13], 0
	v_mfma_f32_16x16x32_bf16 v[56:59], v[64:67], v[14:17], v[56:59]
	v_mfma_f32_16x16x32_bf16 v[60:63], v[68:71], v[14:17], v[60:63]
	s_waitcnt lgkmcnt(0)
	s_nop 7
	v_pk_fma_f32 v[80:81], v[72:73], s[36:37], v[96:97] op_sel_hi:[1,0,0]
	v_pk_fma_f32 v[82:83], v[74:75], s[36:37], v[96:97] op_sel_hi:[1,0,0]
	v_pk_fma_f32 v[84:85], v[76:77], s[36:37], v[96:97] op_sel_hi:[1,0,0]
	v_pk_fma_f32 v[86:87], v[78:79], s[36:37], v[96:97] op_sel_hi:[1,0,0]
	s_nop 0
	v_sub_f32_e32 v80, v80, v161
	v_sub_f32_e32 v81, v81, v161
	v_sub_f32_e32 v82, v82, v161
	v_sub_f32_e32 v83, v83, v161
	v_sub_f32_e32 v84, v84, v161
	v_sub_f32_e32 v85, v85, v161
	v_sub_f32_e32 v86, v86, v161
	v_sub_f32_e32 v87, v87, v161
	v_exp_f32_e32 v80, v80
	v_exp_f32_e32 v81, v81
	v_exp_f32_e32 v82, v82
	v_exp_f32_e32 v83, v83
	v_exp_f32_e32 v84, v84
	v_exp_f32_e32 v85, v85
	v_exp_f32_e32 v86, v86
	v_exp_f32_e32 v87, v87
	s_nop 0
	v_pk_fma_f32 v[88:89], v[56:57], s[36:37], v[96:97] op_sel_hi:[1,0,0]
	v_pk_fma_f32 v[90:91], v[58:59], s[36:37], v[96:97] op_sel_hi:[1,0,0]
	v_pk_fma_f32 v[92:93], v[60:61], s[36:37], v[96:97] op_sel_hi:[1,0,0]
	v_pk_fma_f32 v[94:95], v[62:63], s[36:37], v[96:97] op_sel_hi:[1,0,0]
	s_nop 0
	v_sub_f32_e32 v88, v88, v241
	v_sub_f32_e32 v89, v89, v241
	v_sub_f32_e32 v90, v90, v241
	v_sub_f32_e32 v91, v91, v241
	v_sub_f32_e32 v92, v92, v241
	v_sub_f32_e32 v93, v93, v241
	v_sub_f32_e32 v94, v94, v241
	v_sub_f32_e32 v95, v95, v241
	v_exp_f32_e32 v88, v88
	v_exp_f32_e32 v89, v89
	v_exp_f32_e32 v90, v90
	v_exp_f32_e32 v91, v91
	v_exp_f32_e32 v92, v92
	v_exp_f32_e32 v93, v93
	v_exp_f32_e32 v94, v94
	v_exp_f32_e32 v95, v95
	s_nop 0
	v_mov_b32_e32 v54, v81
	v_mov_b32_e32 v55, v83
	v_mov_b32_e32 v81, v82
	v_pk_mul_f32 v[54:55], v[34:35], v[54:55]
	s_nop 0
	v_pk_fma_f32 v[80:81], v[34:35], v[80:81], v[54:55]
	v_mov_b32_e32 v83, v55
	v_add_f32_e32 v72, v80, v81
	v_mov_b32_e32 v54, v85
	v_mov_b32_e32 v55, v87
	v_mov_b32_e32 v85, v86
	v_pk_mul_f32 v[54:55], v[34:35], v[54:55]
	s_nop 0
	v_pk_fma_f32 v[84:85], v[34:35], v[84:85], v[54:55]
	v_mov_b32_e32 v87, v55
	v_add_f32_e32 v73, v84, v85
	v_mov_b32_e32 v54, v89
	v_mov_b32_e32 v55, v91
	v_mov_b32_e32 v89, v90
	v_pk_mul_f32 v[54:55], v[36:37], v[54:55]
	s_nop 0
	v_pk_fma_f32 v[88:89], v[36:37], v[88:89], v[54:55]
	v_mov_b32_e32 v91, v55
	v_add_f32_e32 v74, v88, v89
	v_mov_b32_e32 v54, v93
	v_mov_b32_e32 v55, v95
	v_mov_b32_e32 v93, v94
	v_pk_mul_f32 v[54:55], v[36:37], v[54:55]
	s_nop 0
	v_pk_fma_f32 v[92:93], v[36:37], v[92:93], v[54:55]
	v_mov_b32_e32 v95, v55
	v_add_f32_e32 v75, v92, v93
	v_cndmask_b32_e64 v76, v83, v31, s[38:39]
	v_cndmask_b32_e64 v77, v87, v83, s[38:39]
	v_cndmask_b32_e64 v78, v91, v23, s[38:39]
	v_cndmask_b32_e64 v79, v95, v91, s[38:39]
	ds_bpermute_b32 v76, v0, v76
	ds_bpermute_b32 v77, v0, v77
	ds_bpermute_b32 v78, v0, v78
	ds_bpermute_b32 v79, v0, v79
	v_mov_b32_e32 v31, v87
	v_mov_b32_e32 v23, v95
	v_add_u32_e32 v54, 32, v49
	v_add_u32_e32 v55, 48, v49
	s_waitcnt lgkmcnt(0)
	v_add_f32_e32 v76, v72, v76
	v_add_f32_e32 v77, v73, v77
	v_add_f32_e32 v78, v74, v78
	v_add_f32_e32 v79, v75, v79
	ds_write2st64_b32 v54, v76, v78 offset1:4
	ds_write2st64_b32 v55, v77, v79 offset1:4
	s_branch .LBB0_365
.Lp2k_p1:
	ds_read_b128 v[56:59], v47
	ds_read_b128 v[64:67], v48
	ds_read_b128 v[60:63], v47 offset:2048
	ds_read_b128 v[68:71], v48 offset:2048
	ds_read2_b32 v[80:81], v50 offset1:16
	ds_read2_b32 v[82:83], v50 offset0:32 offset1:48
	v_add_u32_e32 v54, 0x400, v50
	ds_read2_b32 v[84:85], v54 offset1:16
	ds_read2_b32 v[86:87], v54 offset0:32 offset1:48
	ds_read2_b32 v[88:89], v51 offset1:16
	ds_read2_b32 v[90:91], v51 offset0:32 offset1:48
	v_add_u32_e32 v54, 0x400, v51
	ds_read2_b32 v[92:93], v54 offset1:16
	ds_read2_b32 v[94:95], v54 offset0:32 offset1:48
	s_waitcnt lgkmcnt(8)
	v_mfma_f32_16x16x32_bf16 v[72:75], v[56:59], v[2:5], 0
	v_mfma_f32_16x16x32_bf16 v[76:79], v[60:63], v[2:5], 0
	v_mfma_f32_16x16x32_bf16 v[72:75], v[64:67], v[6:9], v[72:75]
	v_mfma_f32_16x16x32_bf16 v[76:79], v[68:71], v[6:9], v[76:79]
	v_mfma_f32_16x16x32_bf16 v[56:59], v[56:59], v[10:13], 0
	v_mfma_f32_16x16x32_bf16 v[60:63], v[60:63], v[10:13], 0
	v_mfma_f32_16x16x32_bf16 v[56:59], v[64:67], v[14:17], v[56:59]
	v_mfma_f32_16x16x32_bf16 v[60:63], v[68:71], v[14:17], v[60:63]
	s_waitcnt lgkmcnt(0)
	s_nop 7
	v_pk_fma_f32 v[80:81], v[72:73], s[36:37], v[80:81] op_sel_hi:[1,0,1]
	v_pk_fma_f32 v[82:83], v[74:75], s[36:37], v[82:83] op_sel_hi:[1,0,1]
	v_pk_fma_f32 v[84:85], v[76:77], s[36:37], v[84:85] op_sel_hi:[1,0,1]
	v_pk_fma_f32 v[86:87], v[78:79], s[36:37], v[86:87] op_sel_hi:[1,0,1]
	s_nop 0
	v_sub_f32_e32 v80, v80, v161
	v_sub_f32_e32 v81, v81, v161
	v_sub_f32_e32 v82, v82, v161
	v_sub_f32_e32 v83, v83, v161
	v_sub_f32_e32 v84, v84, v161
	v_sub_f32_e32 v85, v85, v161
	v_sub_f32_e32 v86, v86, v161
	v_sub_f32_e32 v87, v87, v161
	v_exp_f32_e32 v80, v80
	v_exp_f32_e32 v81, v81
	v_exp_f32_e32 v82, v82
	v_exp_f32_e32 v83, v83
	v_exp_f32_e32 v84, v84
	v_exp_f32_e32 v85, v85
	v_exp_f32_e32 v86, v86
	v_exp_f32_e32 v87, v87
	s_nop 0
	v_pk_fma_f32 v[88:89], v[56:57], s[36:37], v[88:89] op_sel_hi:[1,0,1]
	v_pk_fma_f32 v[90:91], v[58:59], s[36:37], v[90:91] op_sel_hi:[1,0,1]
	v_pk_fma_f32 v[92:93], v[60:61], s[36:37], v[92:93] op_sel_hi:[1,0,1]
	v_pk_fma_f32 v[94:95], v[62:63], s[36:37], v[94:95] op_sel_hi:[1,0,1]
	s_nop 0
	v_sub_f32_e32 v88, v88, v241
	v_sub_f32_e32 v89, v89, v241
	v_sub_f32_e32 v90, v90, v241
	v_sub_f32_e32 v91, v91, v241
	v_sub_f32_e32 v92, v92, v241
	v_sub_f32_e32 v93, v93, v241
	v_sub_f32_e32 v94, v94, v241
	v_sub_f32_e32 v95, v95, v241
	v_exp_f32_e32 v88, v88
	v_exp_f32_e32 v89, v89
	v_exp_f32_e32 v90, v90
	v_exp_f32_e32 v91, v91
	v_exp_f32_e32 v92, v92
	v_exp_f32_e32 v93, v93
	v_exp_f32_e32 v94, v94
	v_exp_f32_e32 v95, v95
	s_nop 0
	v_mov_b32_e32 v54, v81
	v_mov_b32_e32 v55, v83
	v_mov_b32_e32 v81, v82
	v_pk_mul_f32 v[54:55], v[34:35], v[54:55]
	s_nop 0
	v_pk_fma_f32 v[80:81], v[34:35], v[80:81], v[54:55]
	v_mov_b32_e32 v83, v55
	v_add_f32_e32 v72, v80, v81
	v_mov_b32_e32 v54, v85
	v_mov_b32_e32 v55, v87
	v_mov_b32_e32 v85, v86
	v_pk_mul_f32 v[54:55], v[34:35], v[54:55]
	s_nop 0
	v_pk_fma_f32 v[84:85], v[34:35], v[84:85], v[54:55]
	v_mov_b32_e32 v87, v55
	v_add_f32_e32 v73, v84, v85
	v_mov_b32_e32 v54, v89
	v_mov_b32_e32 v55, v91
	v_mov_b32_e32 v89, v90
	v_pk_mul_f32 v[54:55], v[36:37], v[54:55]
	s_nop 0
	v_pk_fma_f32 v[88:89], v[36:37], v[88:89], v[54:55]
	v_mov_b32_e32 v91, v55
	v_add_f32_e32 v74, v88, v89
	v_mov_b32_e32 v54, v93
	v_mov_b32_e32 v55, v95
	v_mov_b32_e32 v93, v94
	v_pk_mul_f32 v[54:55], v[36:37], v[54:55]
	s_nop 0
	v_pk_fma_f32 v[92:93], v[36:37], v[92:93], v[54:55]
	v_mov_b32_e32 v95, v55
	v_add_f32_e32 v75, v92, v93
	v_cndmask_b32_e64 v76, v83, v31, s[38:39]
	v_cndmask_b32_e64 v77, v87, v83, s[38:39]
	v_cndmask_b32_e64 v78, v91, v23, s[38:39]
	v_cndmask_b32_e64 v79, v95, v91, s[38:39]
	ds_bpermute_b32 v76, v0, v76
	ds_bpermute_b32 v77, v0, v77
	ds_bpermute_b32 v78, v0, v78
	ds_bpermute_b32 v79, v0, v79
	v_mov_b32_e32 v31, v87
	v_mov_b32_e32 v23, v95
	v_mov_b32_e32 v54, v49
	v_add_u32_e32 v55, 16, v49
	s_waitcnt lgkmcnt(0)
	v_add_f32_e32 v76, v72, v76
	v_add_f32_e32 v77, v73, v77
	v_add_f32_e32 v78, v74, v78
	v_add_f32_e32 v79, v75, v79
	ds_write2st64_b32 v54, v76, v78 offset1:4
	ds_write2st64_b32 v55, v77, v79 offset1:4
	ds_read_b128 v[56:59], v47 offset:4096
	ds_read_b128 v[64:67], v48 offset:4096
	ds_read_b128 v[60:63], v47 offset:6144
	ds_read_b128 v[68:71], v48 offset:6144
	v_add_u32_e32 v54, 0x800, v50
	ds_read2_b32 v[80:81], v54 offset1:16
	ds_read2_b32 v[82:83], v54 offset0:32 offset1:48
	v_add_u32_e32 v54, 0xc00, v50
	ds_read2_b32 v[84:85], v54 offset1:16
	ds_read2_b32 v[86:87], v54 offset0:32 offset1:48
	v_add_u32_e32 v54, 0x800, v51
	ds_read2_b32 v[88:89], v54 offset1:16
	ds_read2_b32 v[90:91], v54 offset0:32 offset1:48
	v_add_u32_e32 v54, 0xc00, v51
	ds_read2_b32 v[92:93], v54 offset1:16
	ds_read2_b32 v[94:95], v54 offset0:32 offset1:48
	s_waitcnt lgkmcnt(8)
	v_mfma_f32_16x16x32_bf16 v[72:75], v[56:59], v[2:5], 0
	v_mfma_f32_16x16x32_bf16 v[76:79], v[60:63], v[2:5], 0
	v_mfma_f32_16x16x32_bf16 v[72:75], v[64:67], v[6:9], v[72:75]
	v_mfma_f32_16x16x32_bf16 v[76:79], v[68:71], v[6:9], v[76:79]
	v_mfma_f32_16x16x32_bf16 v[56:59], v[56:59], v[10:13], 0
	v_mfma_f32_16x16x32_bf16 v[60:63], v[60:63], v[10:13], 0
	v_mfma_f32_16x16x32_bf16 v[56:59], v[64:67], v[14:17], v[56:59]
	v_mfma_f32_16x16x32_bf16 v[60:63], v[68:71], v[14:17], v[60:63]
	s_waitcnt lgkmcnt(0)
	s_nop 7
	v_pk_fma_f32 v[80:81], v[72:73], s[36:37], v[80:81] op_sel_hi:[1,0,1]
	v_pk_fma_f32 v[82:83], v[74:75], s[36:37], v[82:83] op_sel_hi:[1,0,1]
	v_pk_fma_f32 v[84:85], v[76:77], s[36:37], v[84:85] op_sel_hi:[1,0,1]
	v_pk_fma_f32 v[86:87], v[78:79], s[36:37], v[86:87] op_sel_hi:[1,0,1]
	s_nop 0
	v_sub_f32_e32 v80, v80, v161
	v_sub_f32_e32 v81, v81, v161
	v_sub_f32_e32 v82, v82, v161
	v_sub_f32_e32 v83, v83, v161
	v_sub_f32_e32 v84, v84, v161
	v_sub_f32_e32 v85, v85, v161
	v_sub_f32_e32 v86, v86, v161
	v_sub_f32_e32 v87, v87, v161
	v_exp_f32_e32 v80, v80
	v_exp_f32_e32 v81, v81
	v_exp_f32_e32 v82, v82
	v_exp_f32_e32 v83, v83
	v_exp_f32_e32 v84, v84
	v_exp_f32_e32 v85, v85
	v_exp_f32_e32 v86, v86
	v_exp_f32_e32 v87, v87
	s_nop 0
	v_pk_fma_f32 v[88:89], v[56:57], s[36:37], v[88:89] op_sel_hi:[1,0,1]
	v_pk_fma_f32 v[90:91], v[58:59], s[36:37], v[90:91] op_sel_hi:[1,0,1]
	v_pk_fma_f32 v[92:93], v[60:61], s[36:37], v[92:93] op_sel_hi:[1,0,1]
	v_pk_fma_f32 v[94:95], v[62:63], s[36:37], v[94:95] op_sel_hi:[1,0,1]
	s_nop 0
	v_sub_f32_e32 v88, v88, v241
	v_sub_f32_e32 v89, v89, v241
	v_sub_f32_e32 v90, v90, v241
	v_sub_f32_e32 v91, v91, v241
	v_sub_f32_e32 v92, v92, v241
	v_sub_f32_e32 v93, v93, v241
	v_sub_f32_e32 v94, v94, v241
	v_sub_f32_e32 v95, v95, v241
	v_exp_f32_e32 v88, v88
	v_exp_f32_e32 v89, v89
	v_exp_f32_e32 v90, v90
	v_exp_f32_e32 v91, v91
	v_exp_f32_e32 v92, v92
	v_exp_f32_e32 v93, v93
	v_exp_f32_e32 v94, v94
	v_exp_f32_e32 v95, v95
	s_nop 0
	v_mov_b32_e32 v54, v81
	v_mov_b32_e32 v55, v83
	v_mov_b32_e32 v81, v82
	v_pk_mul_f32 v[54:55], v[34:35], v[54:55]
	s_nop 0
	v_pk_fma_f32 v[80:81], v[34:35], v[80:81], v[54:55]
	v_mov_b32_e32 v83, v55
	v_add_f32_e32 v72, v80, v81
	v_mov_b32_e32 v54, v85
	v_mov_b32_e32 v55, v87
	v_mov_b32_e32 v85, v86
	v_pk_mul_f32 v[54:55], v[34:35], v[54:55]
	s_nop 0
	v_pk_fma_f32 v[84:85], v[34:35], v[84:85], v[54:55]
	v_mov_b32_e32 v87, v55
	v_add_f32_e32 v73, v84, v85
	v_mov_b32_e32 v54, v89
	v_mov_b32_e32 v55, v91
	v_mov_b32_e32 v89, v90
	v_pk_mul_f32 v[54:55], v[36:37], v[54:55]
	s_nop 0
	v_pk_fma_f32 v[88:89], v[36:37], v[88:89], v[54:55]
	v_mov_b32_e32 v91, v55
	v_add_f32_e32 v74, v88, v89
	v_mov_b32_e32 v54, v93
	v_mov_b32_e32 v55, v95
	v_mov_b32_e32 v93, v94
	v_pk_mul_f32 v[54:55], v[36:37], v[54:55]
	s_nop 0
	v_pk_fma_f32 v[92:93], v[36:37], v[92:93], v[54:55]
	v_mov_b32_e32 v95, v55
	v_add_f32_e32 v75, v92, v93
	v_cndmask_b32_e64 v76, v83, v31, s[38:39]
	v_cndmask_b32_e64 v77, v87, v83, s[38:39]
	v_cndmask_b32_e64 v78, v91, v23, s[38:39]
	v_cndmask_b32_e64 v79, v95, v91, s[38:39]
	ds_bpermute_b32 v76, v0, v76
	ds_bpermute_b32 v77, v0, v77
	ds_bpermute_b32 v78, v0, v78
	ds_bpermute_b32 v79, v0, v79
	v_mov_b32_e32 v31, v87
	v_mov_b32_e32 v23, v95
	v_add_u32_e32 v54, 32, v49
	v_add_u32_e32 v55, 48, v49
	s_waitcnt lgkmcnt(0)
	v_add_f32_e32 v76, v72, v76
	v_add_f32_e32 v77, v73, v77
	v_add_f32_e32 v78, v74, v78
	v_add_f32_e32 v79, v75, v79
	ds_write2st64_b32 v54, v76, v78 offset1:4
	ds_write2st64_b32 v55, v77, v79 offset1:4
	s_branch .LBB0_365
.Lp2k_p0:
	ds_read_b128 v[56:59], v47
	ds_read_b128 v[64:67], v48
	ds_read_b128 v[60:63], v47 offset:2048
	ds_read_b128 v[68:71], v48 offset:2048
	v_subrev_u32_e32 v80, 31, v41
	v_subrev_u32_e32 v81, 47, v41
	v_subrev_u32_e32 v82, 63, v41
	v_subrev_u32_e32 v83, 79, v41
	v_min_u32_e32 v80, s31, v80
	v_min_u32_e32 v81, s31, v81
	v_min_u32_e32 v82, s31, v82
	v_min_u32_e32 v83, s31, v83
	v_xor_b32_e32 v80, s31, v80
	v_xor_b32_e32 v81, s31, v81
	v_xor_b32_e32 v82, s31, v82
	v_xor_b32_e32 v83, s31, v83
	v_lshl_add_u32 v80, v80, 2, v193
	v_lshl_add_u32 v81, v81, 2, v193
	v_lshl_add_u32 v82, v82, 2, v193
	v_lshl_add_u32 v83, v83, 2, v193
	v_subrev_u32_e32 v84, 287, v41
	v_subrev_u32_e32 v85, 303, v41
	v_subrev_u32_e32 v86, 319, v41
	v_subrev_u32_e32 v87, 335, v41
	v_min_u32_e32 v84, s31, v84
	v_min_u32_e32 v85, s31, v85
	v_min_u32_e32 v86, s31, v86
	v_min_u32_e32 v87, s31, v87
	v_xor_b32_e32 v84, s31, v84
	v_xor_b32_e32 v85, s31, v85
	v_xor_b32_e32 v86, s31, v86
	v_xor_b32_e32 v87, s31, v87
	v_lshl_add_u32 v84, v84, 2, v193
	v_lshl_add_u32 v85, v85, 2, v193
	v_lshl_add_u32 v86, v86, 2, v193
	v_lshl_add_u32 v87, v87, 2, v193
	v_subrev_u32_e32 v88, 27, v41
	v_subrev_u32_e32 v89, 43, v41
	v_subrev_u32_e32 v90, 59, v41
	v_subrev_u32_e32 v91, 75, v41
	v_min_u32_e32 v88, s31, v88
	v_min_u32_e32 v89, s31, v89
	v_min_u32_e32 v90, s31, v90
	v_min_u32_e32 v91, s31, v91
	v_xor_b32_e32 v88, s31, v88
	v_xor_b32_e32 v89, s31, v89
	v_xor_b32_e32 v90, s31, v90
	v_xor_b32_e32 v91, s31, v91
	v_lshl_add_u32 v88, v88, 2, v193
	v_lshl_add_u32 v89, v89, 2, v193
	v_lshl_add_u32 v90, v90, 2, v193
	v_lshl_add_u32 v91, v91, 2, v193
	v_subrev_u32_e32 v92, 283, v41
	v_subrev_u32_e32 v93, 299, v41
	v_subrev_u32_e32 v94, 315, v41
	v_subrev_u32_e32 v95, 331, v41
	v_min_u32_e32 v92, s31, v92
	v_min_u32_e32 v93, s31, v93
	v_min_u32_e32 v94, s31, v94
	v_min_u32_e32 v95, s31, v95
	v_xor_b32_e32 v92, s31, v92
	v_xor_b32_e32 v93, s31, v93
	v_xor_b32_e32 v94, s31, v94
	v_xor_b32_e32 v95, s31, v95
	v_lshl_add_u32 v92, v92, 2, v193
	v_lshl_add_u32 v93, v93, 2, v193
	v_lshl_add_u32 v94, v94, 2, v193
	v_lshl_add_u32 v95, v95, 2, v193
	ds_read_b32 v80, v80
	ds_read_b32 v81, v81
	ds_read_b32 v82, v82
	ds_read_b32 v83, v83
	ds_read_b32 v84, v84
	ds_read_b32 v85, v85
	ds_read_b32 v86, v86
	ds_read_b32 v87, v87
	s_waitcnt lgkmcnt(7)
	ds_read_b32 v88, v88
	ds_read_b32 v89, v89
	ds_read_b32 v90, v90
	ds_read_b32 v91, v91
	ds_read_b32 v92, v92
	ds_read_b32 v93, v93
	ds_read_b32 v94, v94
	ds_read_b32 v95, v95
	v_cmp_gt_u32_e64 s[12:13], s27, v46
	s_sub_i32 s98, s27, 16
	v_cmp_gt_u32_e64 s[6:7], s98, v46
	v_mfma_f32_16x16x32_bf16 v[72:75], v[56:59], v[2:5], 0
	v_mfma_f32_16x16x32_bf16 v[76:79], v[60:63], v[2:5], 0
	v_mfma_f32_16x16x32_bf16 v[72:75], v[64:67], v[6:9], v[72:75]
	v_mfma_f32_16x16x32_bf16 v[76:79], v[68:71], v[6:9], v[76:79]
	v_mfma_f32_16x16x32_bf16 v[56:59], v[56:59], v[10:13], 0
	v_mfma_f32_16x16x32_bf16 v[60:63], v[60:63], v[10:13], 0
	v_mfma_f32_16x16x32_bf16 v[56:59], v[64:67], v[14:17], v[56:59]
	v_mfma_f32_16x16x32_bf16 v[60:63], v[68:71], v[14:17], v[60:63]
	v_subrev_u32_e32 v96, 27, v41
	v_subrev_u32_e32 v97, 43, v41
	v_subrev_u32_e32 v98, 59, v41
	v_subrev_u32_e32 v99, 75, v41
	v_subrev_u32_e32 v100, 283, v41
	v_subrev_u32_e32 v101, 299, v41
	v_subrev_u32_e32 v54, 315, v41
	v_subrev_u32_e32 v55, 331, v41
	v_subrev_u32_e32 v64, 31, v41
	v_subrev_u32_e32 v65, 47, v41
	v_subrev_u32_e32 v66, 63, v41
	v_subrev_u32_e32 v67, 79, v41
	v_subrev_u32_e32 v68, 287, v41
	v_subrev_u32_e32 v69, 303, v41
	v_subrev_u32_e32 v70, 319, v41
	v_subrev_u32_e32 v71, 335, v41
	v_ashrrev_i32_e32 v96, 31, v96
	v_ashrrev_i32_e32 v97, 31, v97
	v_ashrrev_i32_e32 v98, 31, v98
	v_ashrrev_i32_e32 v99, 31, v99
	v_ashrrev_i32_e32 v100, 31, v100
	v_ashrrev_i32_e32 v101, 31, v101
	v_ashrrev_i32_e32 v54, 31, v54
	v_ashrrev_i32_e32 v55, 31, v55
	v_ashrrev_i32_e32 v64, 31, v64
	v_ashrrev_i32_e32 v65, 31, v65
	v_ashrrev_i32_e32 v66, 31, v66
	v_ashrrev_i32_e32 v67, 31, v67
	v_ashrrev_i32_e32 v68, 31, v68
	v_ashrrev_i32_e32 v69, 31, v69
	v_ashrrev_i32_e32 v70, 31, v70
	v_ashrrev_i32_e32 v71, 31, v71
	s_waitcnt lgkmcnt(0)
	v_fmac_f32_e32 v80, 0x3e38aa3b, v72
	v_fmac_f32_e32 v81, 0x3e38aa3b, v73
	v_fmac_f32_e32 v82, 0x3e38aa3b, v74
	v_fmac_f32_e32 v83, 0x3e38aa3b, v75
	v_fmac_f32_e32 v84, 0x3e38aa3b, v76
	v_fmac_f32_e32 v85, 0x3e38aa3b, v77
	v_fmac_f32_e32 v86, 0x3e38aa3b, v78
	v_fmac_f32_e32 v87, 0x3e38aa3b, v79
	v_sub_f32_e32 v80, v80, v161
	v_sub_f32_e32 v81, v81, v161
	v_sub_f32_e32 v82, v82, v161
	v_sub_f32_e32 v83, v83, v161
	v_sub_f32_e32 v84, v84, v161
	v_sub_f32_e32 v85, v85, v161
	v_sub_f32_e32 v86, v86, v161
	v_sub_f32_e32 v87, v87, v161
	v_exp_f32_e32 v80, v80
	v_exp_f32_e32 v81, v81
	v_exp_f32_e32 v82, v82
	v_exp_f32_e32 v83, v83
	v_exp_f32_e32 v84, v84
	v_exp_f32_e32 v85, v85
	v_exp_f32_e32 v86, v86
	v_exp_f32_e32 v87, v87
	s_nop 0
	v_fmac_f32_e32 v88, 0x3e38aa3b, v56
	v_fmac_f32_e32 v89, 0x3e38aa3b, v57
	v_fmac_f32_e32 v90, 0x3e38aa3b, v58
	v_fmac_f32_e32 v91, 0x3e38aa3b, v59
	v_fmac_f32_e32 v92, 0x3e38aa3b, v60
	v_fmac_f32_e32 v93, 0x3e38aa3b, v61
	v_fmac_f32_e32 v94, 0x3e38aa3b, v62
	v_fmac_f32_e32 v95, 0x3e38aa3b, v63
	v_sub_f32_e32 v88, v88, v241
	v_sub_f32_e32 v89, v89, v241
	v_sub_f32_e32 v90, v90, v241
	v_sub_f32_e32 v91, v91, v241
	v_sub_f32_e32 v92, v92, v241
	v_sub_f32_e32 v93, v93, v241
	v_sub_f32_e32 v94, v94, v241
	v_sub_f32_e32 v95, v95, v241
	v_exp_f32_e32 v88, v88
	v_exp_f32_e32 v89, v89
	v_exp_f32_e32 v90, v90
	v_exp_f32_e32 v91, v91
	v_exp_f32_e32 v92, v92
	v_exp_f32_e32 v93, v93
	v_exp_f32_e32 v94, v94
	v_exp_f32_e32 v95, v95
	s_nop 0
	v_mul_f32_e32 v80, v34, v80
	v_mul_f32_e32 v81, v34, v81
	v_mul_f32_e32 v82, v34, v82
	v_mul_f32_e32 v83, v34, v83
	v_bfi_b32 v80, v64, 0, v80
	v_bfi_b32 v81, v65, 0, v81
	v_bfi_b32 v82, v66, 0, v82
	v_bfi_b32 v83, v67, 0, v83
	v_cndmask_b32_e64 v83, 0, v83, s[12:13]
	v_add_f32_e32 v72, v80, v81
	v_add_f32_e32 v72, v72, v82
	v_add_f32_e32 v72, v72, v83
	v_mul_f32_e32 v84, v34, v84
	v_mul_f32_e32 v85, v34, v85
	v_mul_f32_e32 v86, v34, v86
	v_mul_f32_e32 v87, v34, v87
	v_bfi_b32 v84, v68, 0, v84
	v_bfi_b32 v85, v69, 0, v85
	v_bfi_b32 v86, v70, 0, v86
	v_bfi_b32 v87, v71, 0, v87
	v_cndmask_b32_e64 v87, 0, v87, s[6:7]
	v_add_f32_e32 v73, v84, v85
	v_add_f32_e32 v73, v73, v86
	v_add_f32_e32 v73, v73, v87
	v_mul_f32_e32 v88, v36, v88
	v_mul_f32_e32 v89, v36, v89
	v_mul_f32_e32 v90, v36, v90
	v_mul_f32_e32 v91, v36, v91
	v_bfi_b32 v88, v96, 0, v88
	v_bfi_b32 v89, v97, 0, v89
	v_bfi_b32 v90, v98, 0, v90
	v_bfi_b32 v91, v99, 0, v91
	v_cndmask_b32_e64 v91, 0, v91, s[12:13]
	v_add_f32_e32 v74, v88, v89
	v_add_f32_e32 v74, v74, v90
	v_add_f32_e32 v74, v74, v91
	v_mul_f32_e32 v92, v36, v92
	v_mul_f32_e32 v93, v36, v93
	v_mul_f32_e32 v94, v36, v94
	v_mul_f32_e32 v95, v36, v95
	v_bfi_b32 v92, v100, 0, v92
	v_bfi_b32 v93, v101, 0, v93
	v_bfi_b32 v94, v54, 0, v94
	v_bfi_b32 v95, v55, 0, v95
	v_cndmask_b32_e64 v95, 0, v95, s[6:7]
	v_add_f32_e32 v75, v92, v93
	v_add_f32_e32 v75, v75, v94
	v_add_f32_e32 v75, v75, v95
	v_cndmask_b32_e64 v76, v83, v31, s[38:39]
	v_cndmask_b32_e64 v77, v87, v83, s[38:39]
	v_cndmask_b32_e64 v78, v91, v23, s[38:39]
	v_cndmask_b32_e64 v79, v95, v91, s[38:39]
	ds_bpermute_b32 v76, v0, v76
	ds_bpermute_b32 v77, v0, v77
	ds_bpermute_b32 v78, v0, v78
	ds_bpermute_b32 v79, v0, v79
	v_mov_b32_e32 v31, v87
	v_mov_b32_e32 v23, v95
	v_mov_b32_e32 v54, v49
	v_add_u32_e32 v55, 16, v49
	s_waitcnt lgkmcnt(0)
	v_add_f32_e32 v76, v72, v76
	v_add_f32_e32 v77, v73, v77
	v_add_f32_e32 v78, v74, v78
	v_add_f32_e32 v79, v75, v79
	ds_write2st64_b32 v54, v76, v78 offset1:4
	ds_write2st64_b32 v55, v77, v79 offset1:4
	ds_read_b128 v[56:59], v47 offset:4096
	ds_read_b128 v[64:67], v48 offset:4096
	ds_read_b128 v[60:63], v47 offset:6144
	ds_read_b128 v[68:71], v48 offset:6144
	v_subrev_u32_e32 v80, 543, v41
	v_subrev_u32_e32 v81, 559, v41
	v_subrev_u32_e32 v82, 575, v41
	v_subrev_u32_e32 v83, 591, v41
	v_min_u32_e32 v80, s31, v80
	v_min_u32_e32 v81, s31, v81
	v_min_u32_e32 v82, s31, v82
	v_min_u32_e32 v83, s31, v83
	v_xor_b32_e32 v80, s31, v80
	v_xor_b32_e32 v81, s31, v81
	v_xor_b32_e32 v82, s31, v82
	v_xor_b32_e32 v83, s31, v83
	v_lshl_add_u32 v80, v80, 2, v193
	v_lshl_add_u32 v81, v81, 2, v193
	v_lshl_add_u32 v82, v82, 2, v193
	v_lshl_add_u32 v83, v83, 2, v193
	v_subrev_u32_e32 v84, 799, v41
	v_subrev_u32_e32 v85, 815, v41
	v_subrev_u32_e32 v86, 831, v41
	v_subrev_u32_e32 v87, 847, v41
	v_min_u32_e32 v84, s31, v84
	v_min_u32_e32 v85, s31, v85
	v_min_u32_e32 v86, s31, v86
	v_min_u32_e32 v87, s31, v87
	v_xor_b32_e32 v84, s31, v84
	v_xor_b32_e32 v85, s31, v85
	v_xor_b32_e32 v86, s31, v86
	v_xor_b32_e32 v87, s31, v87
	v_lshl_add_u32 v84, v84, 2, v193
	v_lshl_add_u32 v85, v85, 2, v193
	v_lshl_add_u32 v86, v86, 2, v193
	v_lshl_add_u32 v87, v87, 2, v193
	v_subrev_u32_e32 v88, 539, v41
	v_subrev_u32_e32 v89, 555, v41
	v_subrev_u32_e32 v90, 571, v41
	v_subrev_u32_e32 v91, 587, v41
	v_min_u32_e32 v88, s31, v88
	v_min_u32_e32 v89, s31, v89
	v_min_u32_e32 v90, s31, v90
	v_min_u32_e32 v91, s31, v91
	v_xor_b32_e32 v88, s31, v88
	v_xor_b32_e32 v89, s31, v89
	v_xor_b32_e32 v90, s31, v90
	v_xor_b32_e32 v91, s31, v91
	v_lshl_add_u32 v88, v88, 2, v193
	v_lshl_add_u32 v89, v89, 2, v193
	v_lshl_add_u32 v90, v90, 2, v193
	v_lshl_add_u32 v91, v91, 2, v193
	v_subrev_u32_e32 v92, 795, v41
	v_subrev_u32_e32 v93, 811, v41
	v_subrev_u32_e32 v94, 827, v41
	v_subrev_u32_e32 v95, 843, v41
	v_min_u32_e32 v92, s31, v92
	v_min_u32_e32 v93, s31, v93
	v_min_u32_e32 v94, s31, v94
	v_min_u32_e32 v95, s31, v95
	v_xor_b32_e32 v92, s31, v92
	v_xor_b32_e32 v93, s31, v93
	v_xor_b32_e32 v94, s31, v94
	v_xor_b32_e32 v95, s31, v95
	v_lshl_add_u32 v92, v92, 2, v193
	v_lshl_add_u32 v93, v93, 2, v193
	v_lshl_add_u32 v94, v94, 2, v193
	v_lshl_add_u32 v95, v95, 2, v193
	ds_read_b32 v80, v80
	ds_read_b32 v81, v81
	ds_read_b32 v82, v82
	ds_read_b32 v83, v83
	ds_read_b32 v84, v84
	ds_read_b32 v85, v85
	ds_read_b32 v86, v86
	ds_read_b32 v87, v87
	s_waitcnt lgkmcnt(7)
	ds_read_b32 v88, v88
	ds_read_b32 v89, v89
	ds_read_b32 v90, v90
	ds_read_b32 v91, v91
	ds_read_b32 v92, v92
	ds_read_b32 v93, v93
	ds_read_b32 v94, v94
	ds_read_b32 v95, v95
	s_sub_i32 s98, s27, 32
	v_cmp_gt_u32_e64 s[12:13], s98, v46
	s_sub_i32 s98, s27, 48
	v_cmp_gt_u32_e64 s[6:7], s98, v46
	v_mfma_f32_16x16x32_bf16 v[72:75], v[56:59], v[2:5], 0
	v_mfma_f32_16x16x32_bf16 v[76:79], v[60:63], v[2:5], 0
	v_mfma_f32_16x16x32_bf16 v[72:75], v[64:67], v[6:9], v[72:75]
	v_mfma_f32_16x16x32_bf16 v[76:79], v[68:71], v[6:9], v[76:79]
	v_mfma_f32_16x16x32_bf16 v[56:59], v[56:59], v[10:13], 0
	v_mfma_f32_16x16x32_bf16 v[60:63], v[60:63], v[10:13], 0
	v_mfma_f32_16x16x32_bf16 v[56:59], v[64:67], v[14:17], v[56:59]
	v_mfma_f32_16x16x32_bf16 v[60:63], v[68:71], v[14:17], v[60:63]
	v_subrev_u32_e32 v96, 539, v41
	v_subrev_u32_e32 v97, 555, v41
	v_subrev_u32_e32 v98, 571, v41
	v_subrev_u32_e32 v99, 587, v41
	v_subrev_u32_e32 v100, 795, v41
	v_subrev_u32_e32 v101, 811, v41
	v_subrev_u32_e32 v54, 827, v41
	v_subrev_u32_e32 v55, 843, v41
	v_subrev_u32_e32 v64, 543, v41
	v_subrev_u32_e32 v65, 559, v41
	v_subrev_u32_e32 v66, 575, v41
	v_subrev_u32_e32 v67, 591, v41
	v_subrev_u32_e32 v68, 799, v41
	v_subrev_u32_e32 v69, 815, v41
	v_subrev_u32_e32 v70, 831, v41
	v_subrev_u32_e32 v71, 847, v41
	v_ashrrev_i32_e32 v96, 31, v96
	v_ashrrev_i32_e32 v97, 31, v97
	v_ashrrev_i32_e32 v98, 31, v98
	v_ashrrev_i32_e32 v99, 31, v99
	v_ashrrev_i32_e32 v100, 31, v100
	v_ashrrev_i32_e32 v101, 31, v101
	v_ashrrev_i32_e32 v54, 31, v54
	v_ashrrev_i32_e32 v55, 31, v55
	v_ashrrev_i32_e32 v64, 31, v64
	v_ashrrev_i32_e32 v65, 31, v65
	v_ashrrev_i32_e32 v66, 31, v66
	v_ashrrev_i32_e32 v67, 31, v67
	v_ashrrev_i32_e32 v68, 31, v68
	v_ashrrev_i32_e32 v69, 31, v69
	v_ashrrev_i32_e32 v70, 31, v70
	v_ashrrev_i32_e32 v71, 31, v71
	s_waitcnt lgkmcnt(0)
	v_fmac_f32_e32 v80, 0x3e38aa3b, v72
	v_fmac_f32_e32 v81, 0x3e38aa3b, v73
	v_fmac_f32_e32 v82, 0x3e38aa3b, v74
	v_fmac_f32_e32 v83, 0x3e38aa3b, v75
	v_fmac_f32_e32 v84, 0x3e38aa3b, v76
	v_fmac_f32_e32 v85, 0x3e38aa3b, v77
	v_fmac_f32_e32 v86, 0x3e38aa3b, v78
	v_fmac_f32_e32 v87, 0x3e38aa3b, v79
	v_sub_f32_e32 v80, v80, v161
	v_sub_f32_e32 v81, v81, v161
	v_sub_f32_e32 v82, v82, v161
	v_sub_f32_e32 v83, v83, v161
	v_sub_f32_e32 v84, v84, v161
	v_sub_f32_e32 v85, v85, v161
	v_sub_f32_e32 v86, v86, v161
	v_sub_f32_e32 v87, v87, v161
	v_exp_f32_e32 v80, v80
	v_exp_f32_e32 v81, v81
	v_exp_f32_e32 v82, v82
	v_exp_f32_e32 v83, v83
	v_exp_f32_e32 v84, v84
	v_exp_f32_e32 v85, v85
	v_exp_f32_e32 v86, v86
	v_exp_f32_e32 v87, v87
	s_nop 0
	v_fmac_f32_e32 v88, 0x3e38aa3b, v56
	v_fmac_f32_e32 v89, 0x3e38aa3b, v57
	v_fmac_f32_e32 v90, 0x3e38aa3b, v58
	v_fmac_f32_e32 v91, 0x3e38aa3b, v59
	v_fmac_f32_e32 v92, 0x3e38aa3b, v60
	v_fmac_f32_e32 v93, 0x3e38aa3b, v61
	v_fmac_f32_e32 v94, 0x3e38aa3b, v62
	v_fmac_f32_e32 v95, 0x3e38aa3b, v63
	v_sub_f32_e32 v88, v88, v241
	v_sub_f32_e32 v89, v89, v241
	v_sub_f32_e32 v90, v90, v241
	v_sub_f32_e32 v91, v91, v241
	v_sub_f32_e32 v92, v92, v241
	v_sub_f32_e32 v93, v93, v241
	v_sub_f32_e32 v94, v94, v241
	v_sub_f32_e32 v95, v95, v241
	v_exp_f32_e32 v88, v88
	v_exp_f32_e32 v89, v89
	v_exp_f32_e32 v90, v90
	v_exp_f32_e32 v91, v91
	v_exp_f32_e32 v92, v92
	v_exp_f32_e32 v93, v93
	v_exp_f32_e32 v94, v94
	v_exp_f32_e32 v95, v95
	s_nop 0
	v_mul_f32_e32 v80, v34, v80
	v_mul_f32_e32 v81, v34, v81
	v_mul_f32_e32 v82, v34, v82
	v_mul_f32_e32 v83, v34, v83
	v_bfi_b32 v80, v64, 0, v80
	v_bfi_b32 v81, v65, 0, v81
	v_bfi_b32 v82, v66, 0, v82
	v_bfi_b32 v83, v67, 0, v83
	v_cndmask_b32_e64 v83, 0, v83, s[12:13]
	v_add_f32_e32 v72, v80, v81
	v_add_f32_e32 v72, v72, v82
	v_add_f32_e32 v72, v72, v83
	v_mul_f32_e32 v84, v34, v84
	v_mul_f32_e32 v85, v34, v85
	v_mul_f32_e32 v86, v34, v86
	v_mul_f32_e32 v87, v34, v87
	v_bfi_b32 v84, v68, 0, v84
	v_bfi_b32 v85, v69, 0, v85
	v_bfi_b32 v86, v70, 0, v86
	v_bfi_b32 v87, v71, 0, v87
	v_cndmask_b32_e64 v87, 0, v87, s[6:7]
	v_add_f32_e32 v73, v84, v85
	v_add_f32_e32 v73, v73, v86
	v_add_f32_e32 v73, v73, v87
	v_mul_f32_e32 v88, v36, v88
	v_mul_f32_e32 v89, v36, v89
	v_mul_f32_e32 v90, v36, v90
	v_mul_f32_e32 v91, v36, v91
	v_bfi_b32 v88, v96, 0, v88
	v_bfi_b32 v89, v97, 0, v89
	v_bfi_b32 v90, v98, 0, v90
	v_bfi_b32 v91, v99, 0, v91
	v_cndmask_b32_e64 v91, 0, v91, s[12:13]
	v_add_f32_e32 v74, v88, v89
	v_add_f32_e32 v74, v74, v90
	v_add_f32_e32 v74, v74, v91
	v_mul_f32_e32 v92, v36, v92
	v_mul_f32_e32 v93, v36, v93
	v_mul_f32_e32 v94, v36, v94
	v_mul_f32_e32 v95, v36, v95
	v_bfi_b32 v92, v100, 0, v92
	v_bfi_b32 v93, v101, 0, v93
	v_bfi_b32 v94, v54, 0, v94
	v_bfi_b32 v95, v55, 0, v95
	v_cndmask_b32_e64 v95, 0, v95, s[6:7]
	v_add_f32_e32 v75, v92, v93
	v_add_f32_e32 v75, v75, v94
	v_add_f32_e32 v75, v75, v95
	v_cndmask_b32_e64 v76, v83, v31, s[38:39]
	v_cndmask_b32_e64 v77, v87, v83, s[38:39]
	v_cndmask_b32_e64 v78, v91, v23, s[38:39]
	v_cndmask_b32_e64 v79, v95, v91, s[38:39]
	ds_bpermute_b32 v76, v0, v76
	ds_bpermute_b32 v77, v0, v77
	ds_bpermute_b32 v78, v0, v78
	ds_bpermute_b32 v79, v0, v79
	v_mov_b32_e32 v31, v87
	v_mov_b32_e32 v23, v95
	v_add_u32_e32 v54, 32, v49
	v_add_u32_e32 v55, 48, v49
	s_waitcnt lgkmcnt(0)
	v_add_f32_e32 v76, v72, v76
	v_add_f32_e32 v77, v73, v77
	v_add_f32_e32 v78, v74, v78
	v_add_f32_e32 v79, v75, v79
	ds_write2st64_b32 v54, v76, v78 offset1:4
	ds_write2st64_b32 v55, v77, v79 offset1:4
	s_branch .LBB0_365
.Lp2k_inv:
	v_cndmask_b32_e64 v72, 0, v31, s[38:39]
	v_cndmask_b32_e64 v73, 0, v23, s[38:39]
	ds_bpermute_b32 v72, v0, v72
	ds_bpermute_b32 v73, v0, v73
	v_mov_b32_e32 v74, 0
	v_mov_b32_e32 v31, 0
	v_mov_b32_e32 v23, 0
	v_add_u32_e32 v54, 16, v49
	v_add_u32_e32 v55, 32, v49
	v_add_u32_e32 v56, 48, v49
	s_waitcnt lgkmcnt(0)
	v_add_f32_e32 v72, 0, v72
	v_add_f32_e32 v73, 0, v73
	ds_write2st64_b32 v49, v72, v73 offset1:4
	ds_write2st64_b32 v54, v74, v74 offset1:4
	ds_write2st64_b32 v55, v74, v74 offset1:4
	ds_write2st64_b32 v56, v74, v74 offset1:4
	s_branch .LBB0_365
